# GEMM K-loops: counter / exit-test SALU block moved in front of the per-K-tile barrier (back edge rotated out of the compute segment head), 9 loops
# speedup vs baseline: 1.0068x; 1.0068x over previous
.Lnd0_wd:
	s_add_i32 s19, s19, 1
	s_add_i32 s13, s13, 32
	s_add_i32 s18, s18, 0x8000
	s_cmpk_eq_i32 s13, 0x460
	s_waitcnt lgkmcnt(0)
	s_barrier
	s_cbranch_scc1 .LBB0_832

.Lnd2g_wd:
	s_add_i32 s22, s22, 0x8000
	s_cmp_eq_u32 s22, 0x20000
	s_waitcnt lgkmcnt(0)
	s_barrier
	s_cbranch_scc1 .LBB0_1251

.LBB0_1329:
	s_waitcnt vmcnt(8)
	s_add_i32 s34, s34, 1
	s_add_i32 s27, s27, 0x8000
	s_cmp_eq_u32 s13, s34
	s_waitcnt lgkmcnt(0)
	s_barrier
	s_cbranch_scc1 .LBB0_1332

.Lnd1_wd:
	s_add_i32 s24, s24, 1
	s_add_i32 s23, s23, 32
	s_add_i32 s22, s22, 0x8000
	s_cmpk_eq_i32 s23, 0x460
	s_waitcnt lgkmcnt(0)
	s_barrier
	s_cbranch_scc1 .LBB0_1584

.LBB0_1662:
	s_waitcnt vmcnt(8)
	s_add_i32 s30, s30, 1
	s_add_i32 s27, s27, 0x8000
	s_cmp_eq_u32 s13, s30
	s_waitcnt lgkmcnt(0)
	s_barrier
	s_cbranch_scc1 .LBB0_1665

.Lnd2_wd:
	s_add_i32 s12, s12, 1
	s_add_i32 s11, s11, 32
	s_add_i32 s10, s10, 0x8000
	s_cmpk_eq_i32 s11, 0x460
	s_waitcnt lgkmcnt(0)
	s_barrier
	s_cbranch_scc1 .LBB0_1917

.LBB0_2754:
	s_waitcnt vmcnt(8)
	s_add_i32 s26, s26, 1
	s_add_i32 s25, s25, 0x8000
	s_cmp_eq_u32 s11, s26
	s_waitcnt lgkmcnt(0)
	s_barrier
	s_cbranch_scc1 .LBB0_2757

.Lnd3_wd:
	s_add_i32 s22, s22, 1
	s_add_i32 s21, s21, 32
	s_add_i32 s20, s20, 0x8000
	s_cmpk_eq_i32 s21, 0x460
	s_waitcnt lgkmcnt(0)
	s_barrier
	s_cbranch_scc1 .LBB0_3009

.LBB0_3087:
	s_waitcnt vmcnt(8)
	s_add_i32 s27, s27, 1
	s_add_i32 s26, s26, 0x8000
	s_cmp_eq_u32 s13, s27
	s_waitcnt lgkmcnt(0)
	s_barrier
	s_cbranch_scc1 .LBB0_3090
